# gdn_prep L/QK-decay stage: 16 decay factors from four ds_read_b128 and back-to-back exp2/masks instead of 16 exec-masked LDS round trips
# speedup vs baseline: 1.0075x; 1.0075x over previous
; DI void phase_gdn_prep(const Params& p, int l, char* smem) {
;     ...
;         {
;             const int t = tid >> 2, part = tid & 3;
;             float s1 = 0.f, s2 = 0.f;
; #pragma unroll
;             for (int j = 0; j < 16; ++j) { const float a = sq[t * 65 + part * 16 + j], c = sk[t * 65 + part * 16 + j]; s1 += a * a; s2 += c * c; }
;             s1 += __shfl_xor(s1, 1); s1 += __shfl_xor(s1, 2); s2 += __shfl_xor(s2, 1); s2 += __shfl_xor(s2, 2);
;             const float r1 = rsqrtf(s1 + 1e-6f) * 0.125f, r2 = rsqrtf(s2 + 1e-6f);
; #pragma unroll
;             for (int j = 0; j < 16; ++j) { sq[t * 65 + part * 16 + j] *= r1; sk[t * 65 + part * 16 + j] *= r2; }
;         }
;         __syncthreads();
.LBB0_281:
	s_or_b64 exec, exec, s[88:89]
	v_add_u32_e32 v39, 0x4118, v118
	s_waitcnt lgkmcnt(0)
	s_barrier
	v_add_u32_e32 v59, 0x4100, v118
	v_add_u32_e32 v58, 0x4108, v118
	v_add_u32_e32 v38, 0x4110, v118
	ds_read2_b32 v[0:1], v118 offset1:1
	ds_read2_b32 v[2:3], v118 offset0:2 offset1:3
	ds_read2_b32 v[4:5], v118 offset0:4 offset1:5
	ds_read2_b32 v[6:7], v118 offset0:6 offset1:7
	ds_read2_b32 v[8:9], v39 offset1:1
	ds_read2_b32 v[10:11], v59 offset1:1
	ds_read2_b32 v[12:13], v58 offset1:1
	ds_read2_b32 v[14:15], v38 offset1:1
	s_waitcnt lgkmcnt(7)
	v_mov_b32_e32 v23, v1
	v_mov_b32_e32 v21, v0
	s_waitcnt lgkmcnt(2)
	v_mov_b32_e32 v22, v11
	v_mov_b32_e32 v20, v10
	v_pk_mul_f32 v[22:23], v[22:23], v[22:23]
	s_waitcnt lgkmcnt(1)
	v_mov_b32_e32 v24, v13
	v_pk_fma_f32 v[20:21], v[20:21], v[20:21], v[22:23]
	v_mov_b32_e32 v22, v12
	v_mov_b32_e32 v23, v2
	v_mov_b32_e32 v25, v3
	v_pk_fma_f32 v[20:21], v[22:23], v[22:23], v[20:21]
	s_waitcnt lgkmcnt(0)
	v_mov_b32_e32 v22, v14
	v_pk_fma_f32 v[20:21], v[24:25], v[24:25], v[20:21]
	v_mov_b32_e32 v23, v4
	v_pk_mul_f32 v[16:17], v[6:7], v[6:7]
	v_pk_mul_f32 v[18:19], v[8:9], v[8:9]
	v_mov_b32_e32 v24, v15
	v_mov_b32_e32 v25, v5
	v_pk_fma_f32 v[20:21], v[22:23], v[22:23], v[20:21]
	v_mov_b32_e32 v22, v18
	v_pk_fma_f32 v[20:21], v[24:25], v[24:25], v[20:21]
	v_mov_b32_e32 v23, v16
	v_pk_add_f32 v[20:21], v[20:21], v[22:23]
	v_mov_b32_e32 v16, v19
	v_add_u32_e32 v61, 0x4120, v118
	ds_read2_b32 v[18:19], v118 offset0:8 offset1:9
	v_pk_add_f32 v[16:17], v[20:21], v[16:17]
	ds_read2_b32 v[20:21], v118 offset0:10 offset1:11
	ds_read2_b32 v[22:23], v118 offset0:12 offset1:13
	ds_read2_b32 v[24:25], v118 offset0:14 offset1:15
	ds_read2_b32 v[28:29], v61 offset1:1
	v_add_u32_e32 v60, 0x4128, v118
	v_add_u32_e32 v37, 0x4130, v118
	v_add_u32_e32 v36, 0x4138, v118
	ds_read2_b32 v[30:31], v60 offset1:1
	ds_read2_b32 v[32:33], v37 offset1:1
	ds_read2_b32 v[34:35], v36 offset1:1
	s_waitcnt lgkmcnt(7)
	v_pk_mul_f32 v[26:27], v[18:19], v[18:19]
	s_waitcnt lgkmcnt(3)
	v_pk_mul_f32 v[186:187], v[28:29], v[28:29]
	v_mov_b32_e32 v205, v26
	v_mov_b32_e32 v204, v186
	v_pk_mul_f32 v[192:193], v[20:21], v[20:21]
	s_waitcnt lgkmcnt(2)
	v_pk_mul_f32 v[194:195], v[30:31], v[30:31]
	v_pk_add_f32 v[16:17], v[16:17], v[204:205]
	v_mov_b32_e32 v26, v187
	v_pk_add_f32 v[16:17], v[16:17], v[26:27]
	v_mov_b32_e32 v26, v194
	v_mov_b32_e32 v27, v192
	v_pk_mul_f32 v[196:197], v[22:23], v[22:23]
	s_waitcnt lgkmcnt(1)
	v_pk_mul_f32 v[198:199], v[32:33], v[32:33]
	v_pk_add_f32 v[16:17], v[16:17], v[26:27]
	v_mov_b32_e32 v192, v195
	v_pk_add_f32 v[16:17], v[16:17], v[192:193]
	v_mov_b32_e32 v26, v198
	v_mov_b32_e32 v27, v196
	v_pk_mul_f32 v[200:201], v[24:25], v[24:25]
	s_waitcnt lgkmcnt(0)
	v_pk_mul_f32 v[202:203], v[34:35], v[34:35]
	v_pk_add_f32 v[16:17], v[16:17], v[26:27]
	v_mov_b32_e32 v196, v199
	v_pk_add_f32 v[16:17], v[16:17], v[196:197]
	v_mov_b32_e32 v26, v202
	v_mov_b32_e32 v27, v200
	v_pk_add_f32 v[16:17], v[16:17], v[26:27]
	v_mov_b32_e32 v200, v203
	v_pk_add_f32 v[16:17], v[16:17], v[200:201]
	ds_bpermute_b32 v27, v65, v17
	ds_bpermute_b32 v26, v65, v16
	s_mov_b32 s4, 0x358637bd
	s_mov_b32 s2, 0x800000
	v_add_u32_e32 v185, v68, v69
	v_add_u32_e32 v186, v68, v70
	s_waitcnt lgkmcnt(0)
	v_pk_add_f32 v[16:17], v[16:17], v[26:27]
	ds_bpermute_b32 v27, v66, v17
	ds_bpermute_b32 v26, v66, v16
	v_readlane_b32 s52, v250, 51
	v_readlane_b32 s60, v250, 59
	v_readlane_b32 s61, v250, 60
	s_mov_b32 s78, 0x800000
	s_waitcnt lgkmcnt(0)
	v_pk_add_f32 v[16:17], v[16:17], v[26:27]
	v_readlane_b32 s53, v250, 52
	v_pk_add_f32 v[16:17], v[16:17], s[4:5] op_sel_hi:[1,0]
	s_mul_i32 s5, s86, 0xa000
	v_mul_f32_e32 v26, 0x4b800000, v17
	v_cmp_gt_f32_e32 vcc, s2, v17
	s_mul_hi_i32 s4, s86, 0xa000
	s_add_u32 s88, s60, s5
	v_cndmask_b32_e32 v17, v17, v26, vcc
	v_rsq_f32_e32 v17, v17
	s_addc_u32 s89, s61, s4
	s_add_u32 s4, s88, 0x2000
	s_addc_u32 s5, s89, 0
	v_mul_f32_e32 v26, 0x45800000, v17
	v_cndmask_b32_e32 v17, v17, v26, vcc
	v_mul_f32_e32 v26, 0x3e000000, v17
	v_pk_mul_f32 v[0:1], v[0:1], v[26:27] op_sel_hi:[1,0]
	ds_write2_b32 v118, v0, v1 offset1:1
	v_pk_mul_f32 v[0:1], v[2:3], v[26:27] op_sel_hi:[1,0]
	ds_write2_b32 v118, v0, v1 offset0:2 offset1:3
	v_pk_mul_f32 v[0:1], v[4:5], v[26:27] op_sel_hi:[1,0]
	v_mul_f32_e32 v2, 0x4b800000, v16
	v_cmp_gt_f32_e32 vcc, s2, v16
	ds_write2_b32 v118, v0, v1 offset0:4 offset1:5
	v_pk_mul_f32 v[0:1], v[6:7], v[26:27] op_sel_hi:[1,0]
	v_cndmask_b32_e32 v2, v16, v2, vcc
	ds_write2_b32 v118, v0, v1 offset0:6 offset1:7
	v_pk_mul_f32 v[0:1], v[18:19], v[26:27] op_sel_hi:[1,0]
	v_rsq_f32_e32 v2, v2
	ds_write2_b32 v118, v0, v1 offset0:8 offset1:9
	v_pk_mul_f32 v[0:1], v[20:21], v[26:27] op_sel_hi:[1,0]
	ds_write2_b32 v118, v0, v1 offset0:10 offset1:11
	v_pk_mul_f32 v[0:1], v[22:23], v[26:27] op_sel_hi:[1,0]
	ds_write2_b32 v118, v0, v1 offset0:12 offset1:13
	v_pk_mul_f32 v[0:1], v[24:25], v[26:27] op_sel_hi:[1,0]
	ds_write2_b32 v118, v0, v1 offset0:14 offset1:15
	v_mul_f32_e32 v0, 0x45800000, v2
	v_cndmask_b32_e32 v0, v2, v0, vcc
	v_pk_mul_f32 v[2:3], v[10:11], v[0:1] op_sel_hi:[1,0]
	ds_write2_b32 v59, v2, v3 offset1:1
	v_pk_mul_f32 v[2:3], v[12:13], v[0:1] op_sel_hi:[1,0]
	ds_write2_b32 v58, v2, v3 offset1:1
	v_pk_mul_f32 v[2:3], v[14:15], v[0:1] op_sel_hi:[1,0]
	ds_write2_b32 v38, v2, v3 offset1:1
	v_pk_mul_f32 v[2:3], v[8:9], v[0:1] op_sel_hi:[1,0]
	ds_write2_b32 v39, v2, v3 offset1:1
	v_pk_mul_f32 v[2:3], v[28:29], v[0:1] op_sel_hi:[1,0]
	ds_write2_b32 v61, v2, v3 offset1:1
	v_pk_mul_f32 v[2:3], v[30:31], v[0:1] op_sel_hi:[1,0]
	ds_write2_b32 v60, v2, v3 offset1:1
	v_pk_mul_f32 v[2:3], v[32:33], v[0:1] op_sel_hi:[1,0]
	v_pk_mul_f32 v[0:1], v[34:35], v[0:1] op_sel_hi:[1,0]
	ds_write2_b32 v37, v2, v3 offset1:1
	ds_write2_b32 v36, v0, v1 offset1:1
	s_waitcnt lgkmcnt(0)
	s_barrier
; DI void phase_gdn_prep(const Params& p, int l, char* smem) {
;     ...
;         f32x4 kkt[4], qkt[4];
;         {
;             char* qb = (char*)sL; char* kb = qb + 8192;
;             {
;                 const int t = tid >> 2, part = tid & 3, sw = (t >> 1) & 7;
;                 u32x4 a0, a1, c0, c1;
; #pragma unroll
;                 for (int j = 0; j < 4; ++j) {
;                     a0[j] = pk2(sq[t * 65 + part * 16 + 2 * j], sq[t * 65 + part * 16 + 2 * j + 1]); a1[j] = pk2(sq[t * 65 + part * 16 + 8 + 2 * j], sq[t * 65 + part * 16 + 9 + 2 * j]);
;                     c0[j] = pk2(sk[t * 65 + part * 16 + 2 * j], sk[t * 65 + part * 16 + 2 * j + 1]); c1[j] = pk2(sk[t * 65 + part * 16 + 8 + 2 * j], sk[t * 65 + part * 16 + 9 + 2 * j]);
;                 }
;                 *(u32x4*)(qb + t * 128 + (((part * 2) ^ sw) << 4)) = a0; *(u32x4*)(qb + t * 128 + (((part * 2 + 1) ^ sw) << 4)) = a1;
;                 *(u32x4*)(kb + t * 128 + (((part * 2) ^ sw) << 4)) = c0; *(u32x4*)(kb + t * 128 + (((part * 2 + 1) ^ sw) << 4)) = c1;
;             }
;             __syncthreads();
;             const int wv = tid >> 6, fr = lane & 15, fq = lane >> 4;
;             const int rc = wv * 16 + fr, swc = (rc >> 1) & 7;
;             bf16x8 kB[2], qB[2];
; #pragma unroll
;             for (int ks = 0; ks < 2; ++ks) {
;                 kB[ks] = *(const bf16x8*)(kb + rc * 128 + (((ks * 4 + fq) ^ swc) << 4));
;                 qB[ks] = *(const bf16x8*)(qb + rc * 128 + (((ks * 4 + fq) ^ swc) << 4));
;             }
; #pragma unroll
;             for (int st = 0; st < 4; ++st) {
;                 const int rs = st * 16 + fr, sws = (rs >> 1) & 7;
;                 const bf16x8 kA0 = *(const bf16x8*)(kb + rs * 128 + (((0 + fq) ^ sws) << 4)), kA1 = *(const bf16x8*)(kb + rs * 128 + (((4 + fq) ^ sws) << 4));
;                 f32x4 z = (f32x4){0.f, 0.f, 0.f, 0.f};
;                 kkt[st] = mfma(kA1, kB[1], mfma(kA0, kB[0], z));
;                 qkt[st] = mfma(kA1, qB[1], mfma(kA0, qB[0], z));
;             }
;         }
;         {
;             const int r = tid >> 2, part = tid & 3;
;             const float eg = __expf(sgc[r]);
;             u32x4 v0, v1, w0, w1;
; #pragma unroll
;             for (int j = 0; j < 8; ++j) {
;                 const int p0 = part * 16 + 2 * j, p1 = p0 + 1;
;                 const unsigned a = pk2(sq[r * 65 + PERM(p0)] * eg, sq[r * 65 + PERM(p1)] * eg);
	ds_read2_b32 v[0:1], v118 offset1:1
	ds_read2_b32 v[2:3], v118 offset0:8 offset1:9
	ds_read2_b32 v[6:7], v118 offset0:2 offset1:3
	ds_read2_b32 v[10:11], v118 offset0:4 offset1:5
	ds_read2_b32 v[16:17], v118 offset0:6 offset1:7
	ds_read2_b32 v[14:15], v118 offset0:10 offset1:11
	ds_read2_b32 v[18:19], v118 offset0:12 offset1:13
	ds_read2_b32 v[20:21], v118 offset0:14 offset1:15
	s_waitcnt lgkmcnt(6)
	v_cvt_pk_bf16_f32 v4, v2, v3
	ds_read2_b32 v[2:3], v59 offset1:1
	ds_read2_b32 v[12:13], v61 offset1:1
	ds_read2_b32 v[22:23], v58 offset1:1
	ds_read2_b32 v[24:25], v38 offset1:1
	ds_read2_b32 v[26:27], v39 offset1:1
	s_waitcnt lgkmcnt(4)
	v_cvt_pk_bf16_f32 v8, v2, v3
	ds_read2_b32 v[2:3], v60 offset1:1
	ds_read2_b32 v[28:29], v37 offset1:1
	ds_read2_b32 v[30:31], v36 offset1:1
	v_cvt_pk_bf16_f32 v0, v0, v1
	s_waitcnt lgkmcnt(6)
	v_cvt_pk_bf16_f32 v12, v12, v13
	v_cvt_pk_bf16_f32 v1, v6, v7
	s_waitcnt lgkmcnt(2)
	v_cvt_pk_bf16_f32 v13, v2, v3
	v_cvt_pk_bf16_f32 v2, v10, v11
	v_cvt_pk_bf16_f32 v3, v16, v17
	v_cvt_pk_bf16_f32 v5, v14, v15
	v_cvt_pk_bf16_f32 v9, v22, v23
	v_cvt_pk_bf16_f32 v6, v18, v19
	v_cvt_pk_bf16_f32 v10, v24, v25
	s_waitcnt lgkmcnt(1)
	v_cvt_pk_bf16_f32 v14, v28, v29
	v_cvt_pk_bf16_f32 v7, v20, v21
	v_cvt_pk_bf16_f32 v11, v26, v27
	s_waitcnt lgkmcnt(0)
	v_cvt_pk_bf16_f32 v15, v30, v31
	ds_write_b128 v163, v[0:3] offset:49920
	ds_write_b128 v164, v[4:7] offset:49920
	ds_write_b128 v163, v[8:11] offset:58112
	ds_write_b128 v164, v[12:15] offset:58112
	s_waitcnt lgkmcnt(0)
	s_barrier
	ds_read_b128 v[0:3], v185 offset:58112
	v_add_u32_e32 v4, v67, v69
	ds_read_b128 v[192:195], v4 offset:58112
	ds_read_b128 v[196:199], v4 offset:49920
	ds_read_b128 v[4:7], v186 offset:58112
	ds_read_b128 v[8:11], v185 offset:60160
	v_add_u32_e32 v16, v67, v70
	s_waitcnt lgkmcnt(3)
	v_mfma_f32_16x16x32_bf16 v[12:15], v[0:3], v[192:195], 0
	ds_read_b128 v[200:203], v16 offset:58112
	ds_read_b128 v[28:31], v16 offset:49920
	ds_read_b128 v[32:35], v186 offset:60160
	v_readlane_b32 s2, v249, 25
	v_readlane_b32 s54, v250, 53
	s_waitcnt lgkmcnt(5)
	v_mfma_f32_16x16x32_bf16 v[0:3], v[0:3], v[196:199], 0
	v_readlane_b32 s55, v250, 54
	v_readlane_b32 s56, v250, 55
	v_readlane_b32 s57, v250, 56
	s_waitcnt lgkmcnt(1)
	v_mfma_f32_16x16x32_bf16 v[20:23], v[4:7], v[28:31], v[0:3]
	v_readlane_b32 s58, v250, 57
	v_readlane_b32 s59, v250, 58
	v_readlane_b32 s62, v250, 61
	v_mfma_f32_16x16x32_bf16 v[0:3], v[8:11], v[192:195], 0
	v_readlane_b32 s63, v250, 62
	v_readlane_b32 s64, v250, 63
	v_readlane_b32 s65, v249, 0
	s_waitcnt lgkmcnt(0)
	v_mfma_f32_16x16x32_bf16 v[16:19], v[32:35], v[200:203], v[0:3]
	v_readlane_b32 s66, v249, 1
	v_readlane_b32 s67, v249, 2
	v_mfma_f32_16x16x32_bf16 v[0:3], v[8:11], v[196:199], 0
	v_mfma_f32_16x16x32_bf16 v[24:27], v[4:7], v[200:203], v[12:15]
	v_mfma_f32_16x16x32_bf16 v[12:15], v[32:35], v[28:31], v[0:3]
	s_nop 5
	ds_read_b128 v[0:3], v185 offset:62208
	ds_read_b128 v[204:207], v185 offset:64256
	ds_read_b128 v[8:11], v186 offset:62208
	ds_read_b128 v[32:35], v186 offset:64256
	v_mov_b32_e32 v185, s2
	s_waitcnt lgkmcnt(3)
	v_mfma_f32_16x16x32_bf16 v[4:7], v[0:3], v[192:195], 0
	v_mfma_f32_16x16x32_bf16 v[0:3], v[0:3], v[196:199], 0
	s_waitcnt lgkmcnt(1)
	v_mfma_f32_16x16x32_bf16 v[4:7], v[8:11], v[200:203], v[4:7]
	v_mfma_f32_16x16x32_bf16 v[8:11], v[8:11], v[28:31], v[0:3]
	v_mfma_f32_16x16x32_bf16 v[0:3], v[204:207], v[192:195], 0
	s_waitcnt lgkmcnt(0)
	v_mfma_f32_16x16x32_bf16 v[0:3], v[32:35], v[200:203], v[0:3]
	ds_read2_b32 v[186:187], v174 offset0:64 offset1:129
	ds_read_b32 v188, v71
	ds_read_b64 v[192:193], v119
	ds_read2_b32 v[200:201], v120 offset1:1
	ds_read_b64 v[202:203], v121
	ds_read_b32 v185, v185
	ds_read_b32 v208, v165 offset:16640
	ds_read_b32 v209, v166 offset:16640
	ds_read_b32 v230, v167 offset:16640
	ds_read_b32 v231, v168 offset:16640
	ds_read_b32 v232, v169 offset:16640
	ds_read_b32 v233, v170 offset:16640
	s_waitcnt lgkmcnt(6)
	v_sub_f32_e32 v191, v185, v192
	v_mul_f32_e32 v191, 0x3fb8aa3b, v191
	v_exp_f32_e32 v234, v191
	v_sub_f32_e32 v191, v185, v193
	v_mul_f32_e32 v191, 0x3fb8aa3b, v191
	v_exp_f32_e32 v235, v191
	v_sub_f32_e32 v191, v185, v202
	v_mul_f32_e32 v191, 0x3fb8aa3b, v191
	v_mul_f32_e32 v188, 0x3fb8aa3b, v188
	v_exp_f32_e32 v202, v191
	v_sub_f32_e32 v191, v185, v203
	v_mfma_f32_16x16x32_bf16 v[192:195], v[204:207], v[196:199], 0
	v_exp_f32_e32 v188, v188
	ds_read2_b32 v[198:199], v175 offset0:64 offset1:129
	v_mul_f32_e32 v191, 0x3fb8aa3b, v191
	v_exp_f32_e32 v203, v191
	v_pk_mul_f32 v[186:187], v[186:187], v[234:235]
	v_mfma_f32_16x16x32_bf16 v[28:31], v[32:35], v[28:31], v[192:195]
	v_cvt_pk_bf16_f32 v196, v186, v187
	v_pk_mul_f32 v[186:187], v[188:189], v[200:201] op_sel_hi:[0,1]
	v_cvt_pk_bf16_f32 v200, v186, v187
	s_waitcnt lgkmcnt(0)
	v_pk_mul_f32 v[186:187], v[198:199], v[202:203]
	ds_read2_b32 v[198:199], v122 offset1:1
	ds_read_b32 v191, v123
	ds_read_b32 v197, v124
	ds_read_b32 v202, v125
	ds_read_b32 v203, v126
	ds_read_b32 v205, v127
	ds_read_b32 v234, v128
	ds_read_b32 v204, v129
	s_waitcnt lgkmcnt(6)
	v_sub_f32_e32 v191, v185, v191
	v_mul_f32_e32 v191, 0x3fb8aa3b, v191
	v_exp_f32_e32 v206, v191
	s_waitcnt lgkmcnt(5)
	v_sub_f32_e32 v191, v185, v197
	v_mul_f32_e32 v191, 0x3fb8aa3b, v191
	v_exp_f32_e32 v207, v191
	s_waitcnt lgkmcnt(2)
	v_sub_f32_e32 v191, v185, v205
	v_cvt_pk_bf16_f32 v197, v186, v187
	v_pk_mul_f32 v[186:187], v[188:189], v[198:199] op_sel_hi:[0,1]
	v_mul_f32_e32 v191, 0x3fb8aa3b, v191
	v_cvt_pk_bf16_f32 v201, v186, v187
	v_pk_mul_f32 v[186:187], v[208:209], v[206:207]
	v_exp_f32_e32 v206, v191
	s_waitcnt lgkmcnt(1)
; DI void phase_gdn_prep(const Params& p, int l, char* smem) {
;     ...
;             *(u32x4*)(rec + 8192 + (r * 64 + part * 16) * 2) = v0; *(u32x4*)(rec + 8192 + (r * 64 + part * 16 + 8) * 2) = v1;
;             *(u32x4*)(rec + 24576 + (r * 64 + part * 16) * 2) = w0; *(u32x4*)(rec + 24576 + (r * 64 + part * 16 + 8) * 2) = w1;
;         }
;         __syncthreads();
;         {
;             const int wv = tid >> 6, fr = lane & 15, fq = lane >> 4;
;             const int c = wv * 16 + fr;
;             const float gcc = sgc[c], bc = sbeta[c];
; #pragma unroll
;             for (int st = 0; st < 4; ++st) {
;                 const int s0 = st * 16 + fq * 4;
;                 f32x4 lv; float qv[4];
; #pragma unroll
;                 for (int ii = 0; ii < 4; ++ii) {
;                     const int s_ = s0 + ii;
;                     const float e = (s_ <= c) ? __expf(gcc - sgc[s_]) : 0.f;
;                     lv[ii] = (s_ < c) ? bc * kkt[st][ii] * e : 0.f;
;                     qv[ii] = qkt[st][ii] * e;
;                 }
	v_sub_f32_e32 v191, v185, v234
	v_mul_f32_e32 v191, 0x3fb8aa3b, v191
	v_exp_f32_e32 v207, v191
	v_cvt_pk_bf16_f32 v198, v186, v187
	v_pk_mul_f32 v[186:187], v[188:189], v[202:203] op_sel_hi:[0,1]
	v_cvt_pk_bf16_f32 v202, v186, v187
	v_pk_mul_f32 v[186:187], v[230:231], v[206:207]
	ds_read_b64 v[206:207], v131
	ds_read2_b32 v[208:209], v176 offset0:64 offset1:129
	ds_read2_b32 v[230:231], v132 offset1:1
	ds_read_b64 v[234:235], v133
	ds_read_b32 v205, v130
	s_waitcnt lgkmcnt(4)
	v_sub_f32_e32 v191, v185, v206
	v_mul_f32_e32 v191, 0x3fb8aa3b, v191
	v_exp_f32_e32 v206, v191
	v_sub_f32_e32 v191, v185, v207
	v_mul_f32_e32 v191, 0x3fb8aa3b, v191
	v_exp_f32_e32 v207, v191
	s_waitcnt lgkmcnt(1)
	v_sub_f32_e32 v191, v185, v234
	v_cvt_pk_bf16_f32 v199, v186, v187
	s_waitcnt lgkmcnt(0)
	v_pk_mul_f32 v[186:187], v[188:189], v[204:205] op_sel_hi:[0,1]
	v_mul_f32_e32 v191, 0x3fb8aa3b, v191
	v_cvt_pk_bf16_f32 v203, v186, v187
	v_pk_mul_f32 v[186:187], v[208:209], v[206:207]
	v_exp_f32_e32 v208, v191
	v_sub_f32_e32 v191, v185, v235
	ds_read2_b32 v[206:207], v177 offset0:64 offset1:129
	v_mul_f32_e32 v191, 0x3fb8aa3b, v191
	v_exp_f32_e32 v209, v191
	v_cvt_pk_bf16_f32 v204, v186, v187
	v_pk_mul_f32 v[186:187], v[188:189], v[230:231] op_sel_hi:[0,1]
	v_cvt_pk_bf16_f32 v230, v186, v187
	s_waitcnt lgkmcnt(0)
	v_pk_mul_f32 v[186:187], v[206:207], v[208:209]
	v_mov_b32_e32 v34, 0
	v_cvt_pk_bf16_f32 v205, v186, v187
	ds_read_b32 v191, v135
	ds_read_b32 v209, v136
	ds_read_b32 v186, v137
	ds_read_b32 v187, v138
	ds_read2_b32 v[206:207], v134 offset1:1
	s_waitcnt lgkmcnt(4)
	v_sub_f32_e32 v191, v185, v191
	v_mul_f32_e32 v191, 0x3fb8aa3b, v191
	ds_read_b64 v[234:235], v139
	v_exp_f32_e32 v208, v191
	s_waitcnt lgkmcnt(4)
	v_sub_f32_e32 v191, v185, v209
	v_mul_f32_e32 v191, 0x3fb8aa3b, v191
	v_exp_f32_e32 v209, v191
	s_waitcnt lgkmcnt(0)
	v_sub_f32_e32 v191, v185, v234
	v_sub_f32_e32 v185, v185, v235
	v_pk_mul_f32 v[206:207], v[188:189], v[206:207] op_sel_hi:[0,1]
	v_mul_f32_e32 v191, 0x3fb8aa3b, v191
	v_mul_f32_e32 v185, 0x3fb8aa3b, v185
	v_cvt_pk_bf16_f32 v231, v206, v207
	v_pk_mul_f32 v[206:207], v[232:233], v[208:209]
	ds_read2_b32 v[208:209], v178 offset0:64 offset1:129
	ds_read2_b32 v[236:237], v140 offset0:16 offset1:17
	v_exp_f32_e32 v234, v191
	v_exp_f32_e32 v235, v185
	v_pk_mul_f32 v[186:187], v[188:189], v[186:187] op_sel_hi:[0,1]
	v_cvt_pk_bf16_f32 v232, v186, v187
	v_cvt_pk_bf16_f32 v206, v206, v207
	s_waitcnt lgkmcnt(1)
	v_pk_mul_f32 v[186:187], v[208:209], v[234:235]
	v_mov_b32_e32 v33, 0
	v_cvt_pk_bf16_f32 v207, v186, v187
	s_waitcnt lgkmcnt(0)
	v_pk_mul_f32 v[186:187], v[188:189], v[236:237] op_sel_hi:[0,1]
	v_cvt_pk_bf16_f32 v233, v186, v187
	v_lshl_add_u64 v[186:187], s[4:5], 0, v[42:43]
	global_store_dwordx4 v[186:187], v[200:203], off
	v_lshl_add_u64 v[186:187], s[4:5], 0, v[44:45]
	s_add_u32 s4, s88, 0x6000
	s_addc_u32 s5, s89, 0
	global_store_dwordx4 v[186:187], v[230:233], off
	v_lshl_add_u64 v[186:187], s[4:5], 0, v[42:43]
	global_store_dwordx4 v[186:187], v[196:199], off
	v_lshl_add_u64 v[186:187], s[4:5], 0, v[44:45]
	global_store_dwordx4 v[186:187], v[204:207], off
	s_barrier
	ds_read_b32 v186, v72
	ds_read_b32 v185, v73
	ds_read_b128 v[98:101], v141
	ds_read_b128 v[102:105], v141 offset:64
	ds_read_b128 v[106:109], v141 offset:128
	ds_read_b128 v[192:195], v141 offset:192
	v_lshrrev_b32_e32 v110, 6, v40
	v_and_b32_e32 v111, 15, v62
	v_lshl_or_b32 v110, v110, 4, v111
	v_lshrrev_b32_e32 v111, 4, v62
	v_lshlrev_b32_e32 v111, 2, v111
	v_sub_u32_e32 v110, v110, v111
	s_waitcnt lgkmcnt(0)
	v_sub_f32_e32 v81, v186, v98
	v_mul_f32_e32 v81, 0x3fb8aa3b, v81
	v_sub_f32_e32 v82, v186, v99
	v_mul_f32_e32 v82, 0x3fb8aa3b, v82
	v_sub_f32_e32 v83, v186, v100
	v_mul_f32_e32 v83, 0x3fb8aa3b, v83
	v_sub_f32_e32 v84, v186, v101
	v_mul_f32_e32 v84, 0x3fb8aa3b, v84
	v_sub_f32_e32 v85, v186, v102
	v_mul_f32_e32 v85, 0x3fb8aa3b, v85
	v_sub_f32_e32 v86, v186, v103
	v_mul_f32_e32 v86, 0x3fb8aa3b, v86
	v_sub_f32_e32 v87, v186, v104
	v_mul_f32_e32 v87, 0x3fb8aa3b, v87
	v_sub_f32_e32 v88, v186, v105
	v_mul_f32_e32 v88, 0x3fb8aa3b, v88
	v_sub_f32_e32 v89, v186, v106
	v_mul_f32_e32 v89, 0x3fb8aa3b, v89
	v_sub_f32_e32 v90, v186, v107
	v_mul_f32_e32 v90, 0x3fb8aa3b, v90
	v_sub_f32_e32 v91, v186, v108
	v_mul_f32_e32 v91, 0x3fb8aa3b, v91
	v_sub_f32_e32 v92, v186, v109
	v_mul_f32_e32 v92, 0x3fb8aa3b, v92
	v_sub_f32_e32 v93, v186, v192
	v_mul_f32_e32 v93, 0x3fb8aa3b, v93
	v_sub_f32_e32 v94, v186, v193
	v_mul_f32_e32 v94, 0x3fb8aa3b, v94
	v_sub_f32_e32 v95, v186, v194
	v_mul_f32_e32 v95, 0x3fb8aa3b, v95
	v_sub_f32_e32 v96, v186, v195
	v_mul_f32_e32 v96, 0x3fb8aa3b, v96
	v_exp_f32_e32 v81, v81
	v_exp_f32_e32 v82, v82
	v_exp_f32_e32 v83, v83
	v_exp_f32_e32 v84, v84
	v_exp_f32_e32 v85, v85
	v_exp_f32_e32 v86, v86
	v_exp_f32_e32 v87, v87
	v_exp_f32_e32 v88, v88
	v_exp_f32_e32 v89, v89
	v_exp_f32_e32 v90, v90
	v_exp_f32_e32 v91, v91
	v_exp_f32_e32 v92, v92
	v_exp_f32_e32 v93, v93
	v_exp_f32_e32 v94, v94
	v_exp_f32_e32 v95, v95
	v_exp_f32_e32 v96, v96
	v_cmp_le_i32_e64 vcc, 0, v110
	v_cmp_le_i32_e64 s[4:5], 1, v110
	v_cmp_le_i32_e64 s[6:7], 2, v110
	v_cndmask_b32_e64 v81, 0, v81, vcc
	v_cmp_le_i32_e64 vcc, 3, v110
	v_cndmask_b32_e64 v82, 0, v82, s[4:5]
	v_cmp_le_i32_e64 s[4:5], 16, v110
	v_cndmask_b32_e64 v83, 0, v83, s[6:7]
	v_cmp_le_i32_e64 s[6:7], 17, v110
	v_cndmask_b32_e64 v84, 0, v84, vcc
	v_cmp_le_i32_e64 vcc, 18, v110
	v_cndmask_b32_e64 v85, 0, v85, s[4:5]
	v_cmp_le_i32_e64 s[4:5], 19, v110
	v_cndmask_b32_e64 v86, 0, v86, s[6:7]
	v_cmp_le_i32_e64 s[6:7], 32, v110
	v_cndmask_b32_e64 v87, 0, v87, vcc
	v_cmp_le_i32_e64 vcc, 33, v110
	v_cndmask_b32_e64 v88, 0, v88, s[4:5]
	v_cmp_le_i32_e64 s[4:5], 34, v110
	v_cndmask_b32_e64 v89, 0, v89, s[6:7]
	v_cmp_le_i32_e64 s[6:7], 35, v110
	v_cndmask_b32_e64 v90, 0, v90, vcc
	v_cmp_le_i32_e64 vcc, 48, v110
	v_cndmask_b32_e64 v91, 0, v91, s[4:5]
	v_cmp_le_i32_e64 s[4:5], 49, v110
	v_cndmask_b32_e64 v92, 0, v92, s[6:7]
	v_cmp_le_i32_e64 s[6:7], 50, v110
	v_cndmask_b32_e64 v93, 0, v93, vcc
	v_cmp_le_i32_e64 vcc, 51, v110
	v_cndmask_b32_e64 v94, 0, v94, s[4:5]
	v_cndmask_b32_e64 v95, 0, v95, s[6:7]
	v_cndmask_b32_e64 v96, 0, v96, vcc
; DI unsigned pk2(float lo, float hi) { f32x2 v = {lo, hi}; bf16x2_t r = __builtin_convertvector(v, bf16x2_t); return __builtin_bit_cast(unsigned, r); }
; DI int PINV(int s) { return (s & ~31) | ((s & 12) << 1) | ((s & 16) >> 2) | (s & 3); }
; DI void phase_gdn_prep(const Params& p, int l, char* smem) {
;     ...
; #pragma unroll
;             for (int st = 0; st < 4; ++st) {
;                 const int s0 = st * 16 + fq * 4;
;                 f32x4 lv; float qv[4];
; #pragma unroll
;                 for (int ii = 0; ii < 4; ++ii) {
;                     const int s_ = s0 + ii;
;                     const float e = (s_ <= c) ? __expf(gcc - sgc[s_]) : 0.f;
;                     lv[ii] = (s_ < c) ? bc * kkt[st][ii] * e : 0.f;
;                     qv[ii] = qkt[st][ii] * e;
;                 }
;                 *(f32x4*)(sL + c * 64 + s0) = lv;
;                 u32x2 o2; o2[0] = pk2(qv[0], qv[1]); o2[1] = pk2(qv[2], qv[3]);
;                 *(u32x2*)(rec + 16384 + (c * 64 + PINV(s0)) * 2) = o2;
;             }
.LBB0_283:
	v_mov_b32_e32 v33, v81
	v_mov_b32_e32 v35, 0
.LBB0_285:
	v_mov_b32_e32 v35, v82
.LBB0_287:
	v_mov_b32_e32 v34, v83
	v_mov_b32_e32 v32, 0
	v_mov_b32_e32 v187, 0
.LBB0_289:
	v_mov_b32_e32 v187, v84
	s_waitcnt lgkmcnt(0)
	v_mul_f32_e32 v25, v25, v185
	v_readlane_b32 s4, v249, 50
	v_mul_f32_e32 v25, v25, v35
	v_readlane_b32 s5, v249, 51
	v_mul_f32_e32 v26, v26, v185
	v_mul_f32_e32 v26, v26, v34
	v_cndmask_b32_e64 v25, 0, v25, s[4:5]
	v_readlane_b32 s4, v249, 54
	v_readlane_b32 s5, v249, 55
	v_mul_f32_e32 v24, v24, v185
	v_mul_f32_e32 v34, v22, v34
	v_cndmask_b32_e64 v26, 0, v26, s[4:5]
	v_mul_f32_e32 v22, v27, v185
	v_readlane_b32 s4, v249, 58
	v_mul_f32_e32 v24, v24, v33
	v_mul_f32_e32 v20, v20, v33
	v_mul_f32_e32 v21, v21, v35
	v_mul_f32_e32 v22, v22, v187
	v_readlane_b32 s5, v249, 59
	v_cndmask_b32_e64 v24, 0, v24, s[10:11]
	v_mul_f32_e32 v23, v23, v187
	v_cndmask_b32_e64 v27, 0, v22, s[4:5]
	v_cvt_pk_bf16_f32 v22, v20, v21
	v_lshl_add_u64 v[20:21], s[88:89], 0, v[56:57]
	ds_write_b128 v145, v[24:27] offset:49920
	v_add_co_u32_e32 v24, vcc, 0x4000, v20
	v_cvt_pk_bf16_f32 v23, v34, v23
	s_nop 0
	v_addc_co_u32_e32 v25, vcc, 0, v21, vcc
	global_store_dwordx2 v[24:25], v[22:23], off
.LBB0_291:
	v_mov_b32_e32 v32, v85
	v_mov_b32_e32 v24, 0
	v_mov_b32_e32 v23, 0
.LBB0_293:
	v_mov_b32_e32 v23, v86
.LBB0_295:
	v_mov_b32_e32 v24, v87
	v_mov_b32_e32 v22, 0
	v_mov_b32_e32 v25, 0
.LBB0_297:
	v_mov_b32_e32 v25, v88
	s_mov_b64 s[4:5], 0x4000
	v_lshl_add_u64 v[20:21], v[20:21], 0, s[4:5]
	v_mul_f32_e32 v16, v16, v185
	v_readlane_b32 s4, v249, 62
	v_mul_f32_e32 v16, v16, v32
	v_readlane_b32 s5, v249, 63
	v_mul_f32_e32 v17, v17, v185
	v_mul_f32_e32 v17, v17, v23
	v_cndmask_b32_e64 v16, 0, v16, s[4:5]
	v_readlane_b32 s4, v248, 2
	v_readlane_b32 s5, v248, 3
	v_mul_f32_e32 v18, v18, v185
	v_mul_f32_e32 v18, v18, v24
	v_cndmask_b32_e64 v17, 0, v17, s[4:5]
	v_readlane_b32 s4, v248, 6
	v_readlane_b32 s5, v248, 7
	v_mul_f32_e32 v19, v19, v185
	v_mul_f32_e32 v14, v14, v24
	v_cndmask_b32_e64 v18, 0, v18, s[4:5]
	v_readlane_b32 s4, v248, 10
	v_mul_f32_e32 v12, v12, v32
	v_mul_f32_e32 v13, v13, v23
	v_mul_f32_e32 v19, v19, v25
	v_readlane_b32 s5, v248, 11
	v_mul_f32_e32 v15, v15, v25
	v_cvt_pk_bf16_f32 v12, v12, v13
	v_cndmask_b32_e64 v19, 0, v19, s[4:5]
	v_cvt_pk_bf16_f32 v13, v14, v15
	ds_write_b128 v145, v[16:19] offset:49984
	global_store_dwordx2 v[20:21], v[12:13], off offset:8
.LBB0_299:
	v_mov_b32_e32 v22, v89
	v_mov_b32_e32 v14, 0
	v_mov_b32_e32 v13, 0
.LBB0_301:
	v_mov_b32_e32 v13, v90
.LBB0_303:
	v_mov_b32_e32 v14, v91
	v_mov_b32_e32 v12, 0
	v_mov_b32_e32 v15, 0
.LBB0_305:
	v_mov_b32_e32 v15, v92
	v_mul_f32_e32 v4, v4, v185
	v_readlane_b32 s4, v248, 14
	v_mul_f32_e32 v4, v4, v22
	v_readlane_b32 s5, v248, 15
	v_mul_f32_e32 v5, v5, v185
	v_mul_f32_e32 v5, v5, v13
	v_cndmask_b32_e64 v4, 0, v4, s[4:5]
	v_readlane_b32 s4, v248, 18
	v_readlane_b32 s5, v248, 19
	v_mul_f32_e32 v6, v6, v185
	v_mul_f32_e32 v7, v7, v185
	v_cndmask_b32_e64 v5, 0, v5, s[4:5]
	v_readlane_b32 s4, v248, 22
	v_mul_f32_e32 v6, v6, v14
	v_readlane_b32 s5, v248, 23
	v_mul_f32_e32 v7, v7, v15
	v_mul_f32_e32 v10, v10, v14
	v_cndmask_b32_e64 v6, 0, v6, s[4:5]
	v_mul_f32_e32 v8, v8, v22
	v_mul_f32_e32 v9, v9, v13
	v_cndmask_b32_e64 v7, 0, v7, s[12:13]
	v_mul_f32_e32 v11, v11, v15
	ds_write_b128 v145, v[4:7] offset:50048
	v_cvt_pk_bf16_f32 v4, v8, v9
	v_cvt_pk_bf16_f32 v5, v10, v11
	global_store_dwordx2 v[20:21], v[4:5], off offset:64
.LBB0_307:
	v_mov_b32_e32 v12, v93
	v_mov_b32_e32 v5, 0
	v_mov_b32_e32 v4, 0
.LBB0_309:
	v_mov_b32_e32 v4, v94
.LBB0_311:
	v_mov_b32_e32 v5, v95
	v_mov_b32_e32 v24, 0
	v_mov_b32_e32 v6, 0
; DI unsigned pk2(float lo, float hi) { f32x2 v = {lo, hi}; bf16x2_t r = __builtin_convertvector(v, bf16x2_t); return __builtin_bit_cast(unsigned, r); }
; DI int PINV(int s) { return (s & ~31) | ((s & 12) << 1) | ((s & 16) >> 2) | (s & 3); }
; DI void phase_gdn_prep(const Params& p, int l, char* smem) {
;     ...
;                 *(f32x4*)(sL + c * 64 + s0) = lv;
;                 u32x2 o2; o2[0] = pk2(qv[0], qv[1]); o2[1] = pk2(qv[2], qv[3]);
;                 *(u32x2*)(rec + 16384 + (c * 64 + PINV(s0)) * 2) = o2;
;             }
;         }
;         {
;             const int t = tid >> 2, part = tid & 3;
;             const float bt = sbeta[t], be = bt * __expf(sgc[t]);
; #pragma unroll
;             for (int j = 0; j < 16; ++j) { sv[t * 65 + part * 16 + j] *= bt; sk[t * 65 + part * 16 + j] *= be; }
;         }
;         __syncthreads();
;         { const int nxt = item + (int)gridDim.x; prefetch(nxt < 3072 ? nxt : item); }
.LBB0_313:
	v_mov_b32_e32 v6, v96
	v_mul_f32_e32 v0, v0, v185
	v_mul_f32_e32 v1, v1, v185
	v_mul_f32_e32 v2, v2, v185
	v_mul_f32_e32 v3, v3, v185
	v_mul_f32_e32 v0, v0, v12
	v_mul_f32_e32 v1, v1, v4
	v_mul_f32_e32 v2, v2, v5
	v_mul_f32_e32 v3, v3, v6
	v_cndmask_b32_e64 v0, 0, v0, s[16:17]
	v_cndmask_b32_e64 v1, 0, v1, s[20:21]
	v_cndmask_b32_e64 v2, 0, v2, s[24:25]
	v_mul_f32_e32 v5, v30, v5
	v_mul_f32_e32 v7, v28, v12
	v_mul_f32_e32 v4, v29, v4
	v_cndmask_b32_e64 v3, 0, v3, s[28:29]
	v_mul_f32_e32 v6, v31, v6
	ds_write_b128 v145, v[0:3] offset:50112
	v_cvt_pk_bf16_f32 v0, v7, v4
	v_cvt_pk_bf16_f32 v1, v5, v6
	global_store_dwordx2 v[20:21], v[0:1], off offset:72
	v_add_u32_e32 v1, 0x8200, v118
	ds_read_b32 v2, v74
	ds_read_b32 v0, v71
	ds_read2_b32 v[4:5], v1 offset0:0 offset1:1
	ds_read2_b32 v[6:7], v1 offset0:2 offset1:3
	ds_read2_b32 v[8:9], v1 offset0:4 offset1:5
	ds_read2_b32 v[10:11], v1 offset0:6 offset1:7
	ds_read2_b32 v[12:13], v1 offset0:8 offset1:9
	ds_read2_b32 v[14:15], v1 offset0:10 offset1:11
	ds_read2_b32 v[16:17], v1 offset0:12 offset1:13
	ds_read2_b32 v[18:19], v1 offset0:14 offset1:15
	v_readlane_b32 s4, v249, 16
	s_add_i32 s30, s86, s4
	s_cmpk_gt_i32 s30, 0xbff
	v_readlane_b32 s5, v249, 17
	s_cselect_b64 s[90:91], -1, 0
	s_cmpk_lt_i32 s30, 0xc00
	s_cselect_b32 s5, s30, s86
	s_ashr_i32 s6, s5, 8
	s_mul_hi_i32 s4, s6, 0x2aaaaaab
	s_lshr_b32 s7, s4, 31
	s_add_i32 s4, s4, s7
	s_mul_i32 s7, s4, 6
	s_lshl_b32 s5, s5, 6
	s_sub_i32 s86, s6, s7
	s_and_b32 s6, s5, 0x3fc0
	s_ashr_i32 s5, s4, 31
	s_sub_i32 s8, 2, s6
	s_lshl_b64 s[92:93], s[4:5], 14
	s_lshl_b32 s94, s86, 6
	v_cmp_lt_i32_e32 vcc, s8, v46
	s_or_b32 s92, s92, s6
	s_ashr_i32 s95, s94, 31
	s_and_b64 s[96:97], s[42:43], vcc
	s_waitcnt lgkmcnt(0)
	ds_read2_b32 v[20:21], v59 offset0:0 offset1:1
	ds_read2_b32 v[22:23], v59 offset0:2 offset1:3
	ds_read2_b32 v[24:25], v59 offset0:4 offset1:5
	ds_read2_b32 v[26:27], v59 offset0:6 offset1:7
	ds_read2_b32 v[28:29], v59 offset0:8 offset1:9
	ds_read2_b32 v[30:31], v59 offset0:10 offset1:11
	ds_read2_b32 v[32:33], v59 offset0:12 offset1:13
	ds_read2_b32 v[34:35], v59 offset0:14 offset1:15
	v_mul_f32_e32 v0, 0x3fb8aa3b, v0
	v_exp_f32_e32 v0, v0
	v_pk_mul_f32 v[4:5], v[2:3], v[4:5] op_sel_hi:[0,1]
	v_pk_mul_f32 v[6:7], v[2:3], v[6:7] op_sel_hi:[0,1]
	v_pk_mul_f32 v[8:9], v[2:3], v[8:9] op_sel_hi:[0,1]
	v_pk_mul_f32 v[10:11], v[2:3], v[10:11] op_sel_hi:[0,1]
	v_pk_mul_f32 v[12:13], v[2:3], v[12:13] op_sel_hi:[0,1]
	v_pk_mul_f32 v[14:15], v[2:3], v[14:15] op_sel_hi:[0,1]
	v_pk_mul_f32 v[16:17], v[2:3], v[16:17] op_sel_hi:[0,1]
	v_pk_mul_f32 v[18:19], v[2:3], v[18:19] op_sel_hi:[0,1]
	v_mul_f32_e32 v0, v2, v0
	s_waitcnt lgkmcnt(0)
	ds_write2_b32 v1, v4, v5 offset0:0 offset1:1
	ds_write2_b32 v1, v6, v7 offset0:2 offset1:3
	ds_write2_b32 v1, v8, v9 offset0:4 offset1:5
	ds_write2_b32 v1, v10, v11 offset0:6 offset1:7
	ds_write2_b32 v1, v12, v13 offset0:8 offset1:9
	ds_write2_b32 v1, v14, v15 offset0:10 offset1:11
	ds_write2_b32 v1, v16, v17 offset0:12 offset1:13
	ds_write2_b32 v1, v18, v19 offset0:14 offset1:15
	v_pk_mul_f32 v[20:21], v[0:1], v[20:21] op_sel_hi:[0,1]
	v_pk_mul_f32 v[22:23], v[0:1], v[22:23] op_sel_hi:[0,1]
	v_pk_mul_f32 v[24:25], v[0:1], v[24:25] op_sel_hi:[0,1]
	v_pk_mul_f32 v[26:27], v[0:1], v[26:27] op_sel_hi:[0,1]
	v_pk_mul_f32 v[28:29], v[0:1], v[28:29] op_sel_hi:[0,1]
	v_pk_mul_f32 v[30:31], v[0:1], v[30:31] op_sel_hi:[0,1]
	v_pk_mul_f32 v[32:33], v[0:1], v[32:33] op_sel_hi:[0,1]
	v_pk_mul_f32 v[34:35], v[0:1], v[34:35] op_sel_hi:[0,1]
	ds_write2_b32 v59, v20, v21 offset0:0 offset1:1
	ds_write2_b32 v59, v22, v23 offset0:2 offset1:3
	ds_write2_b32 v59, v24, v25 offset0:4 offset1:5
	ds_write2_b32 v59, v26, v27 offset0:6 offset1:7
	ds_write2_b32 v59, v28, v29 offset0:8 offset1:9
	ds_write2_b32 v59, v30, v31 offset0:10 offset1:11
	ds_write2_b32 v59, v32, v33 offset0:12 offset1:13
	ds_write2_b32 v59, v34, v35 offset0:14 offset1:15
	v_mov_b32_e32 v24, 0
	v_mov_b32_e32 v25, 0
	v_mov_b32_e32 v26, 0
	v_mov_b32_e32 v27, 0
	s_waitcnt lgkmcnt(0)
	s_barrier
	s_and_saveexec_b64 s[4:5], s[96:97]
	s_cbranch_execz .LBB0_315
	v_readlane_b32 s52, v250, 51
	v_readlane_b32 s56, v250, 55
	v_readlane_b32 s57, v250, 56
	v_lshl_add_u64 v[0:1], s[92:93], 0, v[46:47]
	s_movk_i32 s2, 0x1800
	v_mov_b64_e32 v[2:3], s[56:57]
	v_mad_u64_u32 v[2:3], s[6:7], v0, s2, v[2:3]
	v_mov_b32_e32 v0, v3
	v_mad_u64_u32 v[0:1], s[6:7], v1, s2, v[0:1]
	v_mov_b32_e32 v3, v0
	v_lshl_add_u64 v[0:1], s[94:95], 1, v[2:3]
	v_lshlrev_b32_e32 v188, 1, v48
	v_lshl_add_u64 v[0:1], v[0:1], 0, v[188:189]
	v_add_co_u32_e32 v0, vcc, 0xffffc000, v0
	v_readlane_b32 s53, v250, 52
	s_nop 0
	v_addc_co_u32_e32 v1, vcc, -1, v1, vcc
	global_load_dwordx4 v[24:27], v[0:1], off offset:-2048
	v_readlane_b32 s54, v250, 53
	v_readlane_b32 s55, v250, 54
	v_readlane_b32 s58, v250, 57
	v_readlane_b32 s59, v250, 58
	v_readlane_b32 s60, v250, 59
	v_readlane_b32 s61, v250, 60
	v_readlane_b32 s62, v250, 61
	v_readlane_b32 s63, v250, 62
	v_readlane_b32 s64, v250, 63
	v_readlane_b32 s65, v249, 0
	v_readlane_b32 s66, v249, 1
	v_readlane_b32 s67, v249, 2
